# mode-3 GEMM epilogue: touch-prefetch residual hi/lo lines of row groups 2..7 at epilogue start
# baseline (speedup 1.0000x reference)
;     template <int mode> __device__ __forceinline__ void run(const f32x4 (&acc)[2][2][4][2], const Unit& u, int wr, int wc, int fr, int fq, const LAS float* sc) const {
;     ...
;             const int col0 = u.pn * BM + wc * 32 + 8 * fq;
;             float sA = 1.f, sB = 1.f;
;             if (mode == 4) scales2(u, wr, fr, fq, sA, sB);
;             f32x4 bvv[4];
; #pragma unroll
;             for (int q = 0; q < 4; ++q) bvv[q] = (mode != 4 && bias) ? *(const f32x4*)(bias + col0 + (q >> 1) * HALF + (q & 1) * 4) : (f32x4){0.f, 0.f, 0.f, 0.f};
;             f32x4 xi[2][4]; u32x4 pq[2][2]; u32x4 xh[2][2], xl[2][2];
;             {
;                 const size_t off = (size_t)row0 * D + col0;
; #pragma unroll
;                 for (int bj = 0; bj < 2; ++bj) {
;                     const size_t o = off + bj * HALF;
;                     if (mode == 5) { xi[0][2 * bj] = *(const f32x4*)(xin + o); xi[0][2 * bj + 1] = *(const f32x4*)(xin + o + 4); }
;                     else { xh[0][bj] = *(const u32x4*)(hin + o); xl[0][bj] = *(const u32x4*)(lin + o); }
;                     if (mode == 4) pq[0][bj] = *(const u32x4*)(ob + o);
;                 }
;             }
; #pragma unroll
;             for (int g = 0; g < 8; ++g) {
;                 const int ai = g >> 2, m = g & 3, cb = g & 1, nb = cb ^ 1;
;                 const int row = row0 + ai * HALF + m * 16;
;                 const size_t off = (size_t)row * D + col0;
;                 if (g < 7) {
;                     const size_t offn = (size_t)(row0 + ((g + 1) >> 2) * HALF + ((g + 1) & 3) * 16) * D + col0;
; #pragma unroll
;                     for (int bj = 0; bj < 2; ++bj) {
;                         const size_t o = offn + bj * HALF;
;                         if (mode == 5) { xi[nb][2 * bj] = *(const f32x4*)(xin + o); xi[nb][2 * bj + 1] = *(const f32x4*)(xin + o + 4); }
;                         else { xh[nb][bj] = *(const u32x4*)(hin + o); xl[nb][bj] = *(const u32x4*)(lin + o); }
;                         if (mode == 4) pq[nb][bj] = *(const u32x4*)(ob + o);
;                     }
;                 }
.LBB0_204:
	v_lshl_add_u32 v76, s65, 8, v181
	v_ashrrev_i32_e32 v77, 31, v76
	v_lshlrev_b64 v[138:139], 10, v[76:77]
	v_lshl_add_u64 v[138:139], v[138:139], 0, v[186:187]
	v_lshlrev_b64 v[192:193], 1, v[138:139]
	v_lshl_add_u64 v[138:139], s[34:35], 0, v[192:193]
	global_load_dwordx4 v[170:173], v[138:139], off
	v_lshl_add_u64 v[140:141], s[92:93], 0, v[192:193]
	global_load_dwordx4 v[220:223], v[140:141], off
	global_load_dwordx4 v[166:169], v[138:139], off offset:256
	global_load_dwordx4 v[162:165], v[140:141], off offset:256
	v_or_b32_e32 v188, 16, v76
	v_ashrrev_i32_e32 v189, 31, v188
	v_lshlrev_b64 v[138:139], 10, v[188:189]
	v_lshl_add_u64 v[138:139], v[138:139], 0, v[186:187]
	v_lshlrev_b64 v[190:191], 1, v[138:139]
	v_lshl_add_u64 v[138:139], s[34:35], 0, v[190:191]
	v_lshl_add_u64 v[140:141], s[92:93], 0, v[190:191]
	global_load_dwordx4 v[150:153], v[138:139], off
	global_load_dwordx4 v[146:149], v[140:141], off
	global_load_dwordx4 v[142:145], v[138:139], off offset:256
	s_nop 0
	global_load_dwordx4 v[138:141], v[140:141], off offset:256
	s_add_u32 s98, s34, 0x10000
	s_addc_u32 s99, s35, 0
	v_lshl_add_u64 v[250:251], s[98:99], 0, v[192:193]
	global_load_dword v249, v[250:251], off
	global_load_dword v249, v[250:251], off offset:256
	s_add_u32 s98, s92, 0x10000
	s_addc_u32 s99, s93, 0
	v_lshl_add_u64 v[250:251], s[98:99], 0, v[192:193]
	global_load_dword v249, v[250:251], off
	global_load_dword v249, v[250:251], off offset:256
	s_add_u32 s98, s34, 0x18000
	s_addc_u32 s99, s35, 0
	v_lshl_add_u64 v[250:251], s[98:99], 0, v[192:193]
	global_load_dword v249, v[250:251], off
	global_load_dword v249, v[250:251], off offset:256
	s_add_u32 s98, s92, 0x18000
	s_addc_u32 s99, s93, 0
	v_lshl_add_u64 v[250:251], s[98:99], 0, v[192:193]
	global_load_dword v249, v[250:251], off
	global_load_dword v249, v[250:251], off offset:256
	s_add_u32 s98, s34, 0x40000
	s_addc_u32 s99, s35, 0
	v_lshl_add_u64 v[250:251], s[98:99], 0, v[192:193]
	global_load_dword v249, v[250:251], off
	global_load_dword v249, v[250:251], off offset:256
	s_add_u32 s98, s92, 0x40000
	s_addc_u32 s99, s93, 0
	v_lshl_add_u64 v[250:251], s[98:99], 0, v[192:193]
	global_load_dword v249, v[250:251], off
	global_load_dword v249, v[250:251], off offset:256
	s_add_u32 s98, s34, 0x48000
	s_addc_u32 s99, s35, 0
	v_lshl_add_u64 v[250:251], s[98:99], 0, v[192:193]
	global_load_dword v249, v[250:251], off
	global_load_dword v249, v[250:251], off offset:256
	s_add_u32 s98, s92, 0x48000
	s_addc_u32 s99, s93, 0
	v_lshl_add_u64 v[250:251], s[98:99], 0, v[192:193]
	global_load_dword v249, v[250:251], off
	global_load_dword v249, v[250:251], off offset:256
	s_add_u32 s98, s34, 0x50000
	s_addc_u32 s99, s35, 0
	v_lshl_add_u64 v[250:251], s[98:99], 0, v[192:193]
	global_load_dword v249, v[250:251], off
	global_load_dword v249, v[250:251], off offset:256
	s_add_u32 s98, s92, 0x50000
	s_addc_u32 s99, s93, 0
	v_lshl_add_u64 v[250:251], s[98:99], 0, v[192:193]
	global_load_dword v249, v[250:251], off
	global_load_dword v249, v[250:251], off offset:256
	s_add_u32 s98, s34, 0x58000
	s_addc_u32 s99, s35, 0
	v_lshl_add_u64 v[250:251], s[98:99], 0, v[192:193]
	global_load_dword v249, v[250:251], off
	global_load_dword v249, v[250:251], off offset:256
	s_add_u32 s98, s92, 0x58000
	s_addc_u32 s99, s93, 0
	v_lshl_add_u64 v[250:251], s[98:99], 0, v[192:193]
	global_load_dword v249, v[250:251], off
	global_load_dword v249, v[250:251], off offset:256
	s_mov_b32 s65, s64
	s_lshl_b32 s4, s24, 2
	s_ashr_i32 s5, s4, 31
	s_waitcnt vmcnt(24)
;     template <int mode> __device__ __forceinline__ void run(const f32x4 (&acc)[2][2][4][2], const Unit& u, int wr, int wc, int fr, int fq, const LAS float* sc) const {
;     ...
;                 float s = 1.f;
;                 if (mode == 4) s = __shfl(ai ? sB : sA, m * 16 + fr);
;                 float ss = 0.f;
; #pragma unroll
;                 for (int bj = 0; bj < 2; ++bj) {
;                     u32x4 wh, wl;
; #pragma unroll
;                     for (int n = 0; n < 2; ++n) {
;                         const int q = 2 * bj + n;
;                         const unsigned h0 = n ? xh[cb][bj].z : xh[cb][bj].x, h1 = n ? xh[cb][bj].w : xh[cb][bj].y, l0 = n ? xl[cb][bj].z : xl[cb][bj].x, l1 = n ? xl[cb][bj].w : xl[cb][bj].y;
;                         f32x4 xo;
;                         if (mode == 5) xo = xi[cb][q];
;                         else { xo[0] = bf_lo(h0) + bf_lo(l0); xo[1] = bf_hi(h0) + bf_hi(l0); xo[2] = bf_lo(h1) + bf_lo(l1); xo[3] = bf_hi(h1) + bf_hi(l1); }
;                         f32x4 v;
;                         if (mode != 4) v = xo + acc[ai][bj][m][n] * alpha + bvv[q];
;                         else {
;                             const f32x4 a = acc[ai][bj][m][n] * s;
;                             const unsigned p0 = n ? pq[cb][bj].z : pq[cb][bj].x, p1 = n ? pq[cb][bj].w : pq[cb][bj].y;
;                             v[0] = xo[0] + sigmoidf_(a[0]) * bf_lo(p0); v[1] = xo[1] + sigmoidf_(a[1]) * bf_hi(p0);
;                             v[2] = xo[2] + sigmoidf_(a[2]) * bf_lo(p1); v[3] = xo[3] + sigmoidf_(a[3]) * bf_hi(p1);
;                         }
;                         const unsigned w0 = pk2(v[0], v[1]), w1 = pk2(v[2], v[3]);
;                         const unsigned m0 = pk2(v[0] - bf_lo(w0), v[1] - bf_hi(w0)), m1 = pk2(v[2] - bf_lo(w1), v[3] - bf_hi(w1));
;                         if (n == 0) { wh.x = w0; wh.y = w1; wl.x = m0; wl.y = m1; } else { wh.z = w0; wh.w = w1; wl.z = m0; wl.w = m1; }
;                         ss += (v[0] * v[0] + v[1] * v[1]) + (v[2] * v[2] + v[3] * v[3]);
;                     }
;                     *(u32x4*)(xb + off + bj * HALF) = wh;
;                     *(u32x4*)(lout + off + bj * HALF) = wl;
;                 }
;                 ss += __shfl_xor(ss, 16); ss += __shfl_xor(ss, 32);
;                 if (fq == 0) ssq_out[(size_t)row * 16 + u.pn * 4 + wc] = ss;
	v_lshlrev_b32_e32 v224, 16, v220
	v_lshlrev_b32_e32 v198, 16, v170
	v_and_b32_e32 v199, 0xffff0000, v170
	v_and_b32_e32 v225, 0xffff0000, v220
	v_pk_add_f32 v[198:199], v[198:199], v[224:225]
	v_lshlrev_b32_e32 v170, 16, v171
	v_and_b32_e32 v171, 0xffff0000, v171
	v_lshlrev_b32_e32 v220, 16, v221
	v_and_b32_e32 v221, 0xffff0000, v221
	v_pk_add_f32 v[170:171], v[170:171], v[220:221]
	v_pk_fma_f32 v[158:159], s[54:55], v[158:159], v[198:199]
	v_pk_fma_f32 v[160:161], s[64:65], v[160:161], v[170:171]
	v_pk_add_f32 v[198:199], v[74:75], v[158:159]
	v_pk_add_f32 v[160:161], v[184:185], v[160:161]
	v_cvt_pk_bf16_f32 v170, v198, v199
	s_nop 0
	v_lshlrev_b32_e32 v158, 16, v170
	v_and_b32_e32 v159, 0xffff0000, v170
	v_sub_f32_e32 v158, v198, v158
	v_sub_f32_e32 v159, v199, v159
	v_cvt_pk_bf16_f32 v171, v160, v161
	v_cvt_pk_bf16_f32 v158, v158, v159
	s_nop 0
	v_lshlrev_b32_e32 v159, 16, v171
	v_and_b32_e32 v197, 0xffff0000, v171
	v_sub_f32_e32 v159, v160, v159
	v_sub_f32_e32 v197, v161, v197
	v_cvt_pk_bf16_f32 v159, v159, v197
	v_mul_f32_e32 v197, v199, v199
	v_mul_f32_e32 v161, v161, v161
	v_fmac_f32_e32 v197, v198, v198
	v_fmac_f32_e32 v161, v160, v160
	v_add_f32_e32 v197, v197, v161
	v_lshlrev_b32_e32 v160, 16, v172
	v_and_b32_e32 v161, 0xffff0000, v172
	v_lshlrev_b32_e32 v198, 16, v222
	v_and_b32_e32 v199, 0xffff0000, v222
	v_pk_add_f32 v[160:161], v[160:161], v[198:199]
	v_lshlrev_b32_e32 v172, 16, v173
	v_and_b32_e32 v173, 0xffff0000, v173
	v_lshlrev_b32_e32 v198, 16, v223
	v_and_b32_e32 v199, 0xffff0000, v223
	v_pk_add_f32 v[172:173], v[172:173], v[198:199]
	v_pk_fma_f32 v[154:155], s[54:55], v[154:155], v[160:161]
	v_pk_fma_f32 v[156:157], s[64:65], v[156:157], v[172:173]
	v_pk_add_f32 v[154:155], v[70:71], v[154:155]
	v_pk_add_f32 v[156:157], v[72:73], v[156:157]
	v_cvt_pk_bf16_f32 v172, v154, v155
	s_nop 0
	v_and_b32_e32 v161, 0xffff0000, v172
	v_lshlrev_b32_e32 v160, 16, v172
	v_sub_f32_e32 v161, v155, v161
	v_mul_f32_e32 v155, v155, v155
	v_sub_f32_e32 v160, v154, v160
	v_fmac_f32_e32 v155, v154, v154
	v_mul_f32_e32 v154, v157, v157
	v_cvt_pk_bf16_f32 v173, v156, v157
	v_cvt_pk_bf16_f32 v160, v160, v161
	v_fmac_f32_e32 v154, v156, v156
	v_lshlrev_b32_e32 v161, 16, v173
	v_sub_f32_e32 v161, v156, v161
	v_and_b32_e32 v198, 0xffff0000, v173
	v_add_f32_e32 v154, v155, v154
	v_sub_f32_e32 v198, v157, v198
	v_cvt_pk_bf16_f32 v161, v161, v198
	v_add_f32_e32 v197, v197, v154
	v_lshl_add_u64 v[154:155], s[10:11], 0, v[192:193]
	v_lshl_add_u64 v[156:157], s[28:29], 0, v[192:193]
	global_store_dwordx4 v[154:155], v[170:173], off
	global_store_dwordx4 v[156:157], v[158:161], off
	s_nop 1
	v_lshlrev_b32_e32 v158, 16, v166
	v_and_b32_e32 v159, 0xffff0000, v166
	v_lshlrev_b32_e32 v160, 16, v162
	v_and_b32_e32 v161, 0xffff0000, v162
	v_pk_add_f32 v[158:159], v[158:159], v[160:161]
	v_lshlrev_b32_e32 v160, 16, v167
	v_and_b32_e32 v161, 0xffff0000, v167
	v_lshlrev_b32_e32 v162, 16, v163
	v_and_b32_e32 v163, 0xffff0000, v163
	v_pk_add_f32 v[160:161], v[160:161], v[162:163]
	v_pk_fma_f32 v[134:135], s[54:55], v[134:135], v[158:159]
	v_pk_fma_f32 v[136:137], s[64:65], v[136:137], v[160:161]
	v_pk_add_f32 v[160:161], v[62:63], v[134:135]
	v_pk_add_f32 v[136:137], v[64:65], v[136:137]
	v_cvt_pk_bf16_f32 v134, v160, v161
	v_and_b32_e32 v163, 0xffff0000, v165
	v_cvt_pk_bf16_f32 v135, v136, v137
	v_lshlrev_b32_e32 v158, 16, v134
	v_and_b32_e32 v159, 0xffff0000, v134
	v_and_b32_e32 v162, 0xffff0000, v135
	v_sub_f32_e32 v158, v160, v158
	v_sub_f32_e32 v159, v161, v159
	v_sub_f32_e32 v162, v137, v162
	v_mul_f32_e32 v161, v161, v161
	v_mul_f32_e32 v137, v137, v137
	v_cvt_pk_bf16_f32 v158, v158, v159
	v_lshlrev_b32_e32 v159, 16, v135
	v_fmac_f32_e32 v161, v160, v160
	v_fmac_f32_e32 v137, v136, v136
	v_sub_f32_e32 v159, v136, v159
	v_add_f32_e32 v136, v161, v137
	v_add_f32_e32 v166, v197, v136
	v_lshlrev_b32_e32 v136, 16, v168
	v_and_b32_e32 v137, 0xffff0000, v168
	v_lshlrev_b32_e32 v160, 16, v164
	v_and_b32_e32 v161, 0xffff0000, v164
	v_cvt_pk_bf16_f32 v159, v159, v162
	v_pk_add_f32 v[136:137], v[136:137], v[160:161]
	v_lshlrev_b32_e32 v160, 16, v169
	v_and_b32_e32 v161, 0xffff0000, v169
	v_lshlrev_b32_e32 v162, 16, v165
	v_pk_add_f32 v[160:161], v[160:161], v[162:163]
	v_pk_fma_f32 v[130:131], s[54:55], v[130:131], v[136:137]
	v_pk_fma_f32 v[132:133], s[64:65], v[132:133], v[160:161]
	v_pk_add_f32 v[130:131], v[58:59], v[130:131]
	v_pk_add_f32 v[132:133], v[60:61], v[132:133]
	v_cvt_pk_bf16_f32 v136, v130, v131
	s_nop 0
	v_lshlrev_b32_e32 v160, 16, v136
	v_and_b32_e32 v161, 0xffff0000, v136
	v_sub_f32_e32 v160, v130, v160
	v_sub_f32_e32 v161, v131, v161
	v_mul_f32_e32 v131, v131, v131
	v_cvt_pk_bf16_f32 v137, v132, v133
	v_cvt_pk_bf16_f32 v160, v160, v161
	v_fmac_f32_e32 v131, v130, v130
	v_lshlrev_b32_e32 v161, 16, v137
	v_mul_f32_e32 v130, v133, v133
	v_sub_f32_e32 v161, v132, v161
	v_fmac_f32_e32 v130, v132, v132
	v_and_b32_e32 v132, 64, v205
	v_add_f32_e32 v130, v131, v130
	v_xor_b32_e32 v131, 16, v205
	v_add_u32_e32 v132, 64, v132
	v_cmp_lt_i32_e32 vcc, v131, v132
	v_add_f32_e32 v130, v130, v166
	v_and_b32_e32 v162, 0xffff0000, v137
	v_cndmask_b32_e32 v131, v205, v131, vcc
	v_lshlrev_b32_e32 v166, 2, v131
	ds_bpermute_b32 v131, v166, v130
	v_sub_f32_e32 v162, v133, v162
	v_cvt_pk_bf16_f32 v161, v161, v162
	global_store_dwordx4 v[154:155], v[134:137], off offset:256
	global_store_dwordx4 v[156:157], v[158:161], off offset:256
	s_waitcnt lgkmcnt(0)
	v_add_f32_e32 v130, v130, v131
	v_xor_b32_e32 v131, 32, v205
	v_cmp_lt_i32_e32 vcc, v131, v132
	s_nop 1
	v_cndmask_b32_e32 v131, v205, v131, vcc
	v_lshlrev_b32_e32 v167, 2, v131
	ds_bpermute_b32 v131, v167, v130
	s_and_saveexec_b64 s[44:45], s[40:41]
	s_cbranch_execz .LBB0_206
	v_lshlrev_b64 v[132:133], 6, v[76:77]
	v_lshl_add_u64 v[132:133], s[62:63], 0, v[132:133]
	v_lshl_add_u64 v[132:133], s[4:5], 2, v[132:133]
	s_lshl_b32 s24, s57, 2
	v_lshl_add_u64 v[132:133], v[132:133], 0, s[24:25]
	s_waitcnt lgkmcnt(0)
	v_add_f32_e32 v77, v130, v131
	global_store_dword v[132:133], v77, off

; __global__ void __launch_bounds__(NTHREADS, 2) mk_fwd(Params P_arg) {
	.amdhsa_kernel _Z6mk_fwd6Params
		.amdhsa_group_segment_fixed_size 0
		.amdhsa_private_segment_fixed_size 0
		.amdhsa_kernarg_size 544
		.amdhsa_user_sgpr_count 2
		.amdhsa_user_sgpr_dispatch_ptr 0
		.amdhsa_user_sgpr_queue_ptr 0
		.amdhsa_user_sgpr_kernarg_segment_ptr 1
		.amdhsa_user_sgpr_dispatch_id 0
		.amdhsa_user_sgpr_kernarg_preload_length 0
		.amdhsa_user_sgpr_kernarg_preload_offset 0
		.amdhsa_user_sgpr_private_segment_size 0
		.amdhsa_uses_dynamic_stack 0
		.amdhsa_enable_private_segment 0
		.amdhsa_system_sgpr_workgroup_id_x 1
		.amdhsa_system_sgpr_workgroup_id_y 0
		.amdhsa_system_sgpr_workgroup_id_z 0
		.amdhsa_system_sgpr_workgroup_info 0
		.amdhsa_system_vgpr_workitem_id 2
		.amdhsa_next_free_vgpr 252
		.amdhsa_next_free_sgpr 100
		.amdhsa_accum_offset 252
		.amdhsa_reserve_vcc 1
		.amdhsa_float_round_mode_32 0
		.amdhsa_float_round_mode_16_64 0
		.amdhsa_float_denorm_mode_32 3
		.amdhsa_float_denorm_mode_16_64 3
		.amdhsa_dx10_clamp 1
		.amdhsa_ieee_mode 1
		.amdhsa_fp16_overflow 0
		.amdhsa_tg_split 0
		.amdhsa_exception_fp_ieee_invalid_op 0
		.amdhsa_exception_fp_denorm_src 0
		.amdhsa_exception_fp_ieee_div_zero 0
		.amdhsa_exception_fp_ieee_overflow 0
		.amdhsa_exception_fp_ieee_underflow 0
		.amdhsa_exception_fp_ieee_inexact 0
		.amdhsa_exception_int_div_zero 0
	.end_amdhsa_kernel

; __global__ void __launch_bounds__(NTHREADS, 2) mk_fwd(Params P_arg) {
amdhsa.kernels:
  - .agpr_count:     0
    .args:
      - .offset:         0
        .size:           288
        .value_kind:     by_value
      - .offset:         288
        .size:           4
        .value_kind:     hidden_block_count_x
      - .offset:         292
        .size:           4
        .value_kind:     hidden_block_count_y
      - .offset:         296
        .size:           4
        .value_kind:     hidden_block_count_z
      - .offset:         300
        .size:           2
        .value_kind:     hidden_group_size_x
      - .offset:         302
        .size:           2
        .value_kind:     hidden_group_size_y
      - .offset:         304
        .size:           2
        .value_kind:     hidden_group_size_z
      - .offset:         306
        .size:           2
        .value_kind:     hidden_remainder_x
      - .offset:         308
        .size:           2
        .value_kind:     hidden_remainder_y
      - .offset:         310
        .size:           2
        .value_kind:     hidden_remainder_z
      - .offset:         328
        .size:           8
        .value_kind:     hidden_global_offset_x
      - .offset:         336
        .size:           8
        .value_kind:     hidden_global_offset_y
      - .offset:         344
        .size:           8
        .value_kind:     hidden_global_offset_z
      - .offset:         352
        .size:           2
        .value_kind:     hidden_grid_dims
      - .offset:         376
        .size:           8
        .value_kind:     hidden_multigrid_sync_arg
      - .offset:         408
        .size:           4
        .value_kind:     hidden_dynamic_lds_size
    .group_segment_fixed_size: 0
    .kernarg_segment_align: 8
    .kernarg_segment_size: 544
    .language:       OpenCL C
    .language_version:
      - 2
      - 0
    .max_flat_workgroup_size: 512
    .name:           _Z6mk_fwd6Params
    .private_segment_fixed_size: 0
    .sgpr_count:     106
    .sgpr_spill_count: 174
    .symbol:         _Z6mk_fwd6Params.kd
    .uniform_work_group_size: 1
    .uses_dynamic_stack: false
    .vgpr_count:     252
    .vgpr_spill_count: 0
    .wavefront_size: 64
